# speedup vs baseline: 1.0180x; 1.0121x over previous
.LBB0_988:
	s_or_b64 exec, exec, s[0:1]
	s_add_u32 s10, s60, 0x10000000
	s_addc_u32 s11, s61, 0
	v_mov_b32_e32 v144, v218
	s_waitcnt lgkmcnt(0)
	s_barrier
	s_cmpk_gt_i32 s70, 0x7ff
	v_readfirstlane_b32 s15, v144
	s_cbranch_scc1 .LBB0_1012
	s_and_b32 s99, s70, 7
	s_lshl_b32 s99, s99, 8
	s_add_i32 s99, s99, s70
	s_ashr_i32 s0, s99, 31
	s_lshr_b32 s0, s0, 29
	s_add_i32 s3, s99, s0
	s_and_b32 s0, s3, -8
	s_sub_i32 s2, s99, s0
	s_cmp_gt_i32 s2, -1
	s_cbranch_scc0 .LBB0_991
	s_lshl_b32 s4, s2, 8
	s_cbranch_execz .LBB0_992
	s_branch .LBB0_993

.LBB0_998:
	s_add_i32 s44, s44, 1
	s_and_b32 s98, s70, 7
	s_add_i32 s98, s98, s44
	s_and_b32 s98, s98, 7
	s_mul_i32 s27, s98, s62
	s_add_i32 s27, s27, s70
	s_cmpk_lt_i32 s44, 8
	s_cselect_b64 s[24:25], -1, 0
	s_cmpk_gt_i32 s44, 7
	s_cbranch_scc1 .LBB0_1004
	s_ashr_i32 s26, s27, 31
	s_lshr_b32 s26, s26, 29
	s_add_i32 s28, s27, s26
	s_and_b32 s26, s28, -8
	s_sub_i32 s29, s27, s26
	s_cmp_gt_i32 s29, -1
	s_mov_b64 s[26:27], -1
	s_cbranch_scc0 .LBB0_1001
	s_lshl_b32 s30, s29, 8
	s_mov_b64 s[26:27], 0
